# v15 plus 28 GEMM1 and A2 epilogue store loops software-pipelined by one iteration (next LDS reads issued ahead of the global store; packed data in a quad left dead by the stage write)
# speedup vs baseline: 1.0016x; 1.0016x over previous
.LBB0_641:
	v_mov_b64_e32 v[14:15], v[6:7]
	s_andn2_b64 vcc, exec, s[44:45]
	v_mov_b64_e32 v[12:13], v[4:5]
	v_mov_b64_e32 v[10:11], v[2:3]
	v_mov_b64_e32 v[8:9], v[0:1]
	s_cbranch_vccnz .LBB0_650
	s_cmp_lg_u32 s58, 13
	s_mov_b64 s[44:45], -1
	s_cbranch_scc0 .LBB0_646
	v_mul_f32_e32 v80, 0xbfb8aa3b, v152
	v_exp_f32_e32 v80, v80
	v_mul_f32_e32 v87, 0xbfb8aa3b, v153
	v_exp_f32_e32 v87, v87
	v_mul_f32_e32 v165, 0xbfb8aa3b, v155
	v_add_f32_e32 v80, 1.0, v80
	v_rcp_f32_e32 v164, v80
	v_add_f32_e32 v80, 1.0, v87
	v_mul_f32_e32 v87, 0xbfb8aa3b, v154
	v_exp_f32_e32 v87, v87
	v_exp_f32_e32 v167, v165
	v_rcp_f32_e32 v165, v80
	v_mul_f32_e32 v8, 0xbfb8aa3b, v82
	v_add_f32_e32 v80, 1.0, v87
	v_mul_f32_e32 v87, 0xbfb8aa3b, v156
	v_rcp_f32_e32 v166, v80
	v_add_f32_e32 v80, 1.0, v167
	v_exp_f32_e32 v87, v87
	v_mul_f32_e32 v167, 0xbfb8aa3b, v157
	v_exp_f32_e32 v169, v167
	v_mul_f32_e32 v9, 0xbfb8aa3b, v83
	v_mul_f32_e32 v10, 0xbfb8aa3b, v84
	v_mul_f32_e32 v11, 0xbfb8aa3b, v85
	v_rcp_f32_e32 v167, v80
	v_add_f32_e32 v80, 1.0, v87
	v_mul_f32_e32 v87, 0xbfb8aa3b, v158
	v_exp_f32_e32 v8, v8
	v_exp_f32_e32 v9, v9
	v_exp_f32_e32 v10, v10
	v_exp_f32_e32 v11, v11
	v_mul_f32_e32 v12, 0xbfb8aa3b, v160
	v_mul_f32_e32 v13, 0xbfb8aa3b, v161
	v_mul_f32_e32 v14, 0xbfb8aa3b, v162
	v_mul_f32_e32 v15, 0xbfb8aa3b, v163
	v_rcp_f32_e32 v168, v80
	v_add_f32_e32 v80, 1.0, v169
	v_exp_f32_e32 v87, v87
	v_mul_f32_e32 v169, 0xbfb8aa3b, v159
	v_exp_f32_e32 v12, v12
	v_exp_f32_e32 v13, v13
	v_exp_f32_e32 v14, v14
	v_exp_f32_e32 v15, v15
	v_exp_f32_e32 v171, v169
	v_add_f32_e32 v8, 1.0, v8
	v_add_f32_e32 v9, 1.0, v9
	v_add_f32_e32 v10, 1.0, v10
	v_add_f32_e32 v11, 1.0, v11
	v_rcp_f32_e32 v169, v80
	v_add_f32_e32 v80, 1.0, v87
	v_rcp_f32_e32 v8, v8
	v_rcp_f32_e32 v9, v9
	v_rcp_f32_e32 v10, v10
	v_rcp_f32_e32 v11, v11
	v_add_f32_e32 v12, 1.0, v12
	v_add_f32_e32 v13, 1.0, v13
	v_add_f32_e32 v14, 1.0, v14
	v_add_f32_e32 v15, 1.0, v15
	v_rcp_f32_e32 v170, v80
	v_add_f32_e32 v80, 1.0, v171
	v_rcp_f32_e32 v12, v12
	v_rcp_f32_e32 v13, v13
	v_rcp_f32_e32 v14, v14
	v_rcp_f32_e32 v15, v15
	v_rcp_f32_e32 v171, v80
	v_pk_mul_f32 v[8:9], v[82:83], v[8:9]
	v_pk_mul_f32 v[10:11], v[84:85], v[10:11]
	v_mad_u32_u24 v80, v202, s77, v196
	v_ashrrev_i32_e32 v87, 31, v86
	v_readlane_b32 s36, v254, 54
	s_lshl_b32 s0, s16, 8
	v_readlane_b32 s3, v254, 33
	v_pk_mul_f32 v[12:13], v[160:161], v[12:13]
	v_pk_mul_f32 v[14:15], v[162:163], v[14:15]
	v_pk_mul_f32 v[164:165], v[152:153], v[164:165]
	v_pk_mul_f32 v[166:167], v[154:155], v[166:167]
	v_pk_mul_f32 v[168:169], v[156:157], v[168:169]
	v_pk_mul_f32 v[170:171], v[158:159], v[170:171]
	ds_write_b128 v80, v[8:11]
	ds_write_b128 v80, v[12:15] offset:64
	ds_write_b128 v80, v[164:167] offset:128
	ds_write_b128 v80, v[168:171] offset:192
	v_lshlrev_b64 v[8:9], 11, v[86:87]
	v_readlane_b32 s37, v254, 55
	s_or_b32 s60, s3, s0
	v_and_b32_e32 v10, 7, v194
	v_lshl_add_u64 v[8:9], v[8:9], 0, s[36:37]
	s_lshl_b64 s[36:37], s[60:61], 1
	v_lshlrev_b32_e32 v80, 4, v10
	s_add_u32 s36, s18, s36
	s_nop 1
	v_lshl_add_u64 v[8:9], v[8:9], 0, v[80:81]
	s_addc_u32 s37, s19, s37
	v_lshl_add_u64 v[8:9], s[36:37], 0, v[8:9]
	s_mov_b64 s[36:37], 0x58ff200
	v_mul_lo_u32 v11, v86, s77
	v_lshlrev_b32_e32 v10, 5, v10
	v_lshl_add_u64 v[8:9], v[8:9], 0, s[36:37]
	v_add3_u32 v10, v11, v10, s50
	s_mov_b32 s0, 0
	s_mov_b64 s[36:37], 0x4000
	v_add_u32_e32 v11, s0, v10
	v_add_u32_e32 v12, 0x10000, v11
	v_add_u32_e32 v11, 0x10010, v11
	ds_read_b128 v[12:15], v12
	ds_read_b128 v[164:167], v11
.LBB0_644:
	s_addk_i32 s0, 0x880
	s_waitcnt lgkmcnt(0)
	v_cvt_pk_bf16_f32 v168, v12, v13
	v_cvt_pk_bf16_f32 v169, v14, v15
	v_cvt_pk_bf16_f32 v170, v164, v165
	v_cvt_pk_bf16_f32 v171, v166, v167
	s_min_u32 s101, s0, 0x1980
	v_add_u32_e32 v11, s101, v10
	v_add_u32_e32 v12, 0x10000, v11
	v_add_u32_e32 v11, 0x10010, v11
	ds_read_b128 v[12:15], v12
	ds_read_b128 v[164:167], v11
	s_cmpk_eq_i32 s0, 0x2200
	global_store_dwordx4 v[8:9], v[168:171], off sc1
	s_nop 1
	v_lshl_add_u64 v[8:9], v[8:9], 0, s[36:37]
	s_cbranch_scc0 .LBB0_644
	s_waitcnt lgkmcnt(0)
	s_mov_b64 s[44:45], 0

.LBB0_654:
	s_or_b64 exec, exec, s[44:45]
	s_waitcnt lgkmcnt(0)
	ds_read_b128 v[8:11], v201 offset:256
	ds_read_b128 v[12:15], v201 offset:320
	ds_read_b128 v[164:167], v201 offset:384
	ds_read_b128 v[168:171], v201 offset:448
	s_lshl_b32 s0, s16, 8
	v_readlane_b32 s3, v254, 33
	s_waitcnt lgkmcnt(0)
	v_pk_mul_f32 v[10:11], v[84:85], v[10:11]
	v_pk_mul_f32 v[8:9], v[82:83], v[8:9]
	v_mad_u32_u24 v80, v202, s77, v196
	v_ashrrev_i32_e32 v87, 31, v86
	s_or_b32 s60, s3, s0
	v_pk_mul_f32 v[14:15], v[162:163], v[14:15]
	v_pk_mul_f32 v[12:13], v[160:161], v[12:13]
	v_pk_mul_f32 v[166:167], v[154:155], v[166:167]
	v_pk_mul_f32 v[164:165], v[152:153], v[164:165]
	v_pk_mul_f32 v[170:171], v[158:159], v[170:171]
	v_pk_mul_f32 v[168:169], v[156:157], v[168:169]
	ds_write_b128 v80, v[8:11]
	ds_write_b128 v80, v[12:15] offset:64
	ds_write_b128 v80, v[164:167] offset:128
	ds_write_b128 v80, v[168:171] offset:192
	v_lshlrev_b64 v[8:9], 9, v[86:87]
	v_and_b32_e32 v10, 7, v194
	s_lshl_b64 s[36:37], s[60:61], 1
	v_lshl_add_u64 v[8:9], v[8:9], 0, s[8:9]
	v_lshlrev_b32_e32 v80, 4, v10
	s_add_u32 s36, s18, s36
	v_lshl_add_u64 v[8:9], v[8:9], 0, v[80:81]
	s_addc_u32 s37, s19, s37
	s_nop 1
	v_lshl_add_u64 v[8:9], s[36:37], 0, v[8:9]
	s_mov_b64 s[36:37], 0x51ff500
	v_lshl_add_u64 v[164:165], v[8:9], 0, s[36:37]
	v_mul_lo_u32 v8, v86, s77
	v_lshlrev_b32_e32 v9, 5, v10
	v_add3_u32 v80, v8, v9, s50
	s_mov_b32 s0, 0
	v_add_u32_e32 v8, s0, v80
	v_add_u32_e32 v9, 0x10000, v8
	v_add_u32_e32 v12, 0x10010, v8
	ds_read_b128 v[8:11], v9
	ds_read_b128 v[12:15], v12
.LBB0_655:
	s_addk_i32 s0, 0x880
	s_waitcnt lgkmcnt(0)
	v_cvt_pk_bf16_f32 v168, v8, v9
	v_cvt_pk_bf16_f32 v169, v10, v11
	v_cvt_pk_bf16_f32 v170, v12, v13
	v_cvt_pk_bf16_f32 v171, v14, v15
	s_min_u32 s101, s0, 0x1980
	v_add_u32_e32 v8, s101, v80
	v_add_u32_e32 v9, 0x10000, v8
	v_add_u32_e32 v12, 0x10010, v8
	ds_read_b128 v[8:11], v9
	ds_read_b128 v[12:15], v12
	s_cmpk_eq_i32 s0, 0x2200
	global_store_dwordx4 v[164:165], v[168:171], off sc1
	s_nop 1
	v_lshl_add_u64 v[164:165], v[164:165], 0, s[82:83]
	s_cbranch_scc0 .LBB0_655
	s_waitcnt lgkmcnt(0)
	v_mov_b64_e32 v[14:15], v[6:7]
	v_mov_b64_e32 v[12:13], v[4:5]
	v_mov_b64_e32 v[10:11], v[2:3]
	v_mov_b64_e32 v[8:9], v[0:1]

.LBB0_684:
	v_mad_u32_u24 v80, v202, s77, v196
	ds_write_b128 v80, v[8:11]
	ds_write_b128 v80, v[164:167] offset:64
	ds_write_b128 v80, v[12:15] offset:128
	ds_write_b128 v80, v[168:171] offset:192
	v_mov_b64_e32 v[8:9], s[28:29]
	s_movk_i32 s0, 0x300
	v_mad_i64_i32 v[8:9], s[2:3], v86, s0, v[8:9]
	s_lshl_b32 s0, s16, 8
	v_readlane_b32 s2, v254, 33
	s_or_b32 s60, s2, s0
	v_and_b32_e32 v10, 7, v194
	s_lshl_b64 s[2:3], s[60:61], 1
	v_lshlrev_b32_e32 v80, 4, v10
	s_add_u32 s2, s18, s2
	v_lshl_add_u64 v[8:9], v[8:9], 0, v[80:81]
	s_addc_u32 s3, s19, s3
	s_nop 1
	v_lshl_add_u64 v[8:9], s[2:3], 0, v[8:9]
	s_mov_b64 s[2:3], 0x47ffa00
	v_lshl_add_u64 v[164:165], v[8:9], 0, s[2:3]
	v_mul_lo_u32 v8, v86, s77
	v_lshlrev_b32_e32 v9, 5, v10
	v_add3_u32 v80, v8, v9, s50
	s_mov_b32 s0, 0
	s_mov_b32 s2, 0x3e38aa3b
	v_add_u32_e32 v8, s0, v80
	v_add_u32_e32 v9, 0x10000, v8
	v_add_u32_e32 v12, 0x10010, v8
	ds_read_b128 v[8:11], v9
	ds_read_b128 v[12:15], v12
.LBB0_685:
	s_addk_i32 s0, 0x880
	s_waitcnt lgkmcnt(0)
	v_pk_mul_f32 v[8:9], v[8:9], s[2:3] op_sel_hi:[1,0]
	v_pk_mul_f32 v[10:11], v[10:11], s[2:3] op_sel_hi:[1,0]
	v_pk_mul_f32 v[12:13], v[12:13], s[2:3] op_sel_hi:[1,0]
	v_pk_mul_f32 v[14:15], v[14:15], s[2:3] op_sel_hi:[1,0]
	v_cvt_pk_bf16_f32 v168, v8, v9
	v_cvt_pk_bf16_f32 v169, v10, v11
	v_cvt_pk_bf16_f32 v170, v12, v13
	v_cvt_pk_bf16_f32 v171, v14, v15
	s_min_u32 s101, s0, 0x1980
	v_add_u32_e32 v8, s101, v80
	v_add_u32_e32 v9, 0x10000, v8
	v_add_u32_e32 v12, 0x10010, v8
	ds_read_b128 v[8:11], v9
	ds_read_b128 v[12:15], v12
	s_cmpk_eq_i32 s0, 0x2200
	global_store_dwordx4 v[164:165], v[168:171], off sc1
	s_nop 1
	v_lshl_add_u64 v[164:165], v[164:165], 0, s[72:73]
	s_cbranch_scc0 .LBB0_685
	s_waitcnt lgkmcnt(0)
	v_mov_b64_e32 v[14:15], v[6:7]
	v_mov_b64_e32 v[12:13], v[4:5]
	v_mov_b64_e32 v[10:11], v[2:3]
	v_mov_b64_e32 v[8:9], v[0:1]

.LBB0_687:
	s_andn2_b64 vcc, exec, s[44:45]
	s_cbranch_vccnz .LBB0_690
	s_lshl_b32 s0, s16, 8
	v_readlane_b32 s2, v254, 33
	v_mad_u32_u24 v8, v202, s77, v196
	v_ashrrev_i32_e32 v87, 31, v86
	s_or_b32 s60, s2, s0
	ds_write_b128 v8, v[82:85]
	ds_write_b128 v8, v[160:163] offset:64
	ds_write_b128 v8, v[152:155] offset:128
	ds_write_b128 v8, v[156:159] offset:192
	v_lshlrev_b64 v[8:9], 9, v[86:87]
	v_and_b32_e32 v10, 7, v194
	s_lshl_b64 s[2:3], s[60:61], 1
	v_lshl_add_u64 v[8:9], v[8:9], 0, s[8:9]
	v_lshlrev_b32_e32 v80, 4, v10
	s_add_u32 s2, s18, s2
	v_lshl_add_u64 v[8:9], v[8:9], 0, v[80:81]
	s_addc_u32 s3, s19, s3
	s_nop 1
	v_lshl_add_u64 v[8:9], s[2:3], 0, v[8:9]
	s_mov_b64 s[2:3], 0x43ffc00
	v_lshl_add_u64 v[164:165], v[8:9], 0, s[2:3]
	v_mul_lo_u32 v8, v86, s77
	v_lshlrev_b32_e32 v9, 5, v10
	v_add3_u32 v80, v8, v9, s50
	s_mov_b32 s0, 0
	v_add_u32_e32 v8, s0, v80
	v_add_u32_e32 v9, 0x10000, v8
	v_add_u32_e32 v12, 0x10010, v8
	ds_read_b128 v[8:11], v9
	ds_read_b128 v[12:15], v12
.LBB0_689:
	s_addk_i32 s0, 0x880
	s_waitcnt lgkmcnt(0)
	v_cvt_pk_bf16_f32 v156, v8, v9
	v_cvt_pk_bf16_f32 v157, v10, v11
	v_cvt_pk_bf16_f32 v158, v12, v13
	v_cvt_pk_bf16_f32 v159, v14, v15
	s_min_u32 s101, s0, 0x1980
	v_add_u32_e32 v8, s101, v80
	v_add_u32_e32 v9, 0x10000, v8
	v_add_u32_e32 v12, 0x10010, v8
	ds_read_b128 v[8:11], v9
	ds_read_b128 v[12:15], v12
	s_cmpk_eq_i32 s0, 0x2200
	global_store_dwordx4 v[164:165], v[156:159], off sc1
	s_nop 1
	v_lshl_add_u64 v[164:165], v[164:165], 0, s[82:83]
	s_cbranch_scc0 .LBB0_689
	s_waitcnt lgkmcnt(0)
	v_mov_b64_e32 v[14:15], v[6:7]
	v_mov_b64_e32 v[12:13], v[4:5]
	v_mov_b64_e32 v[10:11], v[2:3]
	v_mov_b64_e32 v[8:9], v[0:1]

.LBB0_695:
	s_lshl_b32 s0, s16, 8
	v_readlane_b32 s2, v254, 33
	v_mad_u32_u24 v80, v202, s77, v196
	v_ashrrev_i32_e32 v87, 31, v86
	s_or_b32 s60, s2, s0
	ds_write_b128 v80, v[8:11]
	ds_write_b128 v80, v[12:15] offset:64
	ds_write_b128 v80, v[164:167] offset:128
	ds_write_b128 v80, v[168:171] offset:192
	v_lshlrev_b64 v[8:9], 9, v[86:87]
	v_and_b32_e32 v10, 7, v194
	s_lshl_b64 s[2:3], s[60:61], 1
	v_lshl_add_u64 v[8:9], v[8:9], 0, s[8:9]
	v_lshlrev_b32_e32 v80, 4, v10
	s_add_u32 s2, s18, s2
	v_lshl_add_u64 v[8:9], v[8:9], 0, v[80:81]
	s_addc_u32 s3, s19, s3
	s_nop 1
	v_lshl_add_u64 v[8:9], s[2:3], 0, v[8:9]
	s_mov_b64 s[2:3], 0x3fffe00
	v_lshl_add_u64 v[164:165], v[8:9], 0, s[2:3]
	v_mul_lo_u32 v8, v86, s77
	v_lshlrev_b32_e32 v9, 5, v10
	v_add3_u32 v80, v8, v9, s50
	s_mov_b32 s0, 0
	s_mov_b32 s2, 0x3e000000
	v_add_u32_e32 v8, s0, v80
	v_add_u32_e32 v9, 0x10000, v8
	v_add_u32_e32 v12, 0x10010, v8
	ds_read_b128 v[8:11], v9
	ds_read_b128 v[12:15], v12
.LBB0_696:
	s_addk_i32 s0, 0x880
	s_waitcnt lgkmcnt(0)
	v_pk_mul_f32 v[8:9], v[8:9], s[2:3] op_sel_hi:[1,0]
	v_pk_mul_f32 v[10:11], v[10:11], s[2:3] op_sel_hi:[1,0]
	v_pk_mul_f32 v[12:13], v[12:13], s[2:3] op_sel_hi:[1,0]
	v_pk_mul_f32 v[14:15], v[14:15], s[2:3] op_sel_hi:[1,0]
	v_cvt_pk_bf16_f32 v168, v8, v9
	v_cvt_pk_bf16_f32 v169, v10, v11
	v_cvt_pk_bf16_f32 v170, v12, v13
	v_cvt_pk_bf16_f32 v171, v14, v15
	s_min_u32 s101, s0, 0x1980
	v_add_u32_e32 v8, s101, v80
	v_add_u32_e32 v9, 0x10000, v8
	v_add_u32_e32 v12, 0x10010, v8
	ds_read_b128 v[8:11], v9
	ds_read_b128 v[12:15], v12
	s_cmpk_eq_i32 s0, 0x2200
	global_store_dwordx4 v[164:165], v[168:171], off sc1
	s_nop 1
	v_lshl_add_u64 v[164:165], v[164:165], 0, s[82:83]
	s_cbranch_scc0 .LBB0_696
	s_waitcnt lgkmcnt(0)
	v_mov_b64_e32 v[14:15], v[6:7]
	v_mov_b64_e32 v[12:13], v[4:5]
	v_mov_b64_e32 v[10:11], v[2:3]
	v_mov_b64_e32 v[8:9], v[0:1]

.LBB0_701:
	s_lshl_b32 s0, s16, 8
	v_readlane_b32 s2, v254, 33
	s_or_b32 s2, s2, s0
	v_mad_u32_u24 v8, v202, s77, v196
	v_ashrrev_i32_e32 v87, 31, v86
	s_ashr_i32 s3, s2, 31
	ds_write_b128 v8, v[82:85]
	ds_write_b128 v8, v[160:163] offset:64
	ds_write_b128 v8, v[152:155] offset:128
	ds_write_b128 v8, v[156:159] offset:192
	v_lshlrev_b64 v[8:9], 9, v[86:87]
	v_and_b32_e32 v10, 7, v194
	s_lshl_b64 s[2:3], s[2:3], 1
	v_lshl_add_u64 v[8:9], v[8:9], 0, s[8:9]
	v_lshlrev_b32_e32 v80, 4, v10
	s_add_u32 s2, s18, s2
	s_nop 1
	v_lshl_add_u64 v[8:9], v[8:9], 0, v[80:81]
	s_addc_u32 s3, s19, s3
	v_lshl_add_u64 v[8:9], s[2:3], 0, v[8:9]
	s_mov_b64 s[2:3], 0x3c00000
	v_mul_lo_u32 v11, v86, s77
	v_lshlrev_b32_e32 v10, 5, v10
	v_lshl_add_u64 v[8:9], v[8:9], 0, s[2:3]
	v_add3_u32 v10, v11, v10, s50
	s_mov_b32 s0, 0
	v_add_u32_e32 v11, s0, v10
	v_add_u32_e32 v12, 0x10000, v11
	v_add_u32_e32 v11, 0x10010, v11
	ds_read_b128 v[12:15], v12
	ds_read_b128 v[82:85], v11
.LBB0_702:
	s_addk_i32 s0, 0x880
	s_waitcnt lgkmcnt(0)
	v_cvt_pk_bf16_f32 v156, v12, v13
	v_cvt_pk_bf16_f32 v157, v14, v15
	v_cvt_pk_bf16_f32 v158, v82, v83
	v_cvt_pk_bf16_f32 v159, v84, v85
	s_min_u32 s101, s0, 0x1980
	v_add_u32_e32 v11, s101, v10
	v_add_u32_e32 v12, 0x10000, v11
	v_add_u32_e32 v11, 0x10010, v11
	ds_read_b128 v[12:15], v12
	ds_read_b128 v[82:85], v11
	s_cmpk_eq_i32 s0, 0x2200
	global_store_dwordx4 v[8:9], v[156:159], off sc1
	s_nop 1
	v_lshl_add_u64 v[8:9], v[8:9], 0, s[82:83]
	s_cbranch_scc0 .LBB0_702
	s_waitcnt lgkmcnt(0)
	v_mov_b64_e32 v[14:15], v[6:7]
	v_mov_b64_e32 v[12:13], v[4:5]
	v_mov_b64_e32 v[10:11], v[2:3]
	v_mov_b64_e32 v[8:9], v[0:1]

.LBB0_777:
	v_mov_b64_e32 v[14:15], v[6:7]
	s_andn2_b64 vcc, exec, s[44:45]
	v_mov_b64_e32 v[12:13], v[4:5]
	v_mov_b64_e32 v[10:11], v[2:3]
	v_mov_b64_e32 v[8:9], v[0:1]
	s_cbranch_vccnz .LBB0_786
	s_cmp_lg_u32 s58, 13
	s_mov_b64 s[44:45], -1
	s_cbranch_scc0 .LBB0_782
	v_mul_f32_e32 v80, 0xbfb8aa3b, v152
	v_exp_f32_e32 v80, v80
	v_mul_f32_e32 v87, 0xbfb8aa3b, v153
	v_exp_f32_e32 v87, v87
	v_mul_f32_e32 v165, 0xbfb8aa3b, v155
	v_add_f32_e32 v80, 1.0, v80
	v_rcp_f32_e32 v164, v80
	v_add_f32_e32 v80, 1.0, v87
	v_mul_f32_e32 v87, 0xbfb8aa3b, v154
	v_exp_f32_e32 v87, v87
	v_exp_f32_e32 v167, v165
	v_rcp_f32_e32 v165, v80
	v_mul_f32_e32 v8, 0xbfb8aa3b, v82
	v_add_f32_e32 v80, 1.0, v87
	v_mul_f32_e32 v87, 0xbfb8aa3b, v156
	v_rcp_f32_e32 v166, v80
	v_add_f32_e32 v80, 1.0, v167
	v_exp_f32_e32 v87, v87
	v_mul_f32_e32 v167, 0xbfb8aa3b, v157
	v_exp_f32_e32 v169, v167
	v_mul_f32_e32 v9, 0xbfb8aa3b, v83
	v_mul_f32_e32 v10, 0xbfb8aa3b, v84
	v_mul_f32_e32 v11, 0xbfb8aa3b, v85
	v_rcp_f32_e32 v167, v80
	v_add_f32_e32 v80, 1.0, v87
	v_mul_f32_e32 v87, 0xbfb8aa3b, v158
	v_exp_f32_e32 v8, v8
	v_exp_f32_e32 v9, v9
	v_exp_f32_e32 v10, v10
	v_exp_f32_e32 v11, v11
	v_mul_f32_e32 v12, 0xbfb8aa3b, v160
	v_mul_f32_e32 v13, 0xbfb8aa3b, v161
	v_mul_f32_e32 v14, 0xbfb8aa3b, v162
	v_mul_f32_e32 v15, 0xbfb8aa3b, v163
	v_rcp_f32_e32 v168, v80
	v_add_f32_e32 v80, 1.0, v169
	v_exp_f32_e32 v87, v87
	v_mul_f32_e32 v169, 0xbfb8aa3b, v159
	v_exp_f32_e32 v12, v12
	v_exp_f32_e32 v13, v13
	v_exp_f32_e32 v14, v14
	v_exp_f32_e32 v15, v15
	v_exp_f32_e32 v171, v169
	v_add_f32_e32 v8, 1.0, v8
	v_add_f32_e32 v9, 1.0, v9
	v_add_f32_e32 v10, 1.0, v10
	v_add_f32_e32 v11, 1.0, v11
	v_rcp_f32_e32 v169, v80
	v_add_f32_e32 v80, 1.0, v87
	v_rcp_f32_e32 v8, v8
	v_rcp_f32_e32 v9, v9
	v_rcp_f32_e32 v10, v10
	v_rcp_f32_e32 v11, v11
	v_add_f32_e32 v12, 1.0, v12
	v_add_f32_e32 v13, 1.0, v13
	v_add_f32_e32 v14, 1.0, v14
	v_add_f32_e32 v15, 1.0, v15
	v_rcp_f32_e32 v170, v80
	v_add_f32_e32 v80, 1.0, v171
	v_rcp_f32_e32 v12, v12
	v_rcp_f32_e32 v13, v13
	v_rcp_f32_e32 v14, v14
	v_rcp_f32_e32 v15, v15
	v_rcp_f32_e32 v171, v80
	v_pk_mul_f32 v[8:9], v[82:83], v[8:9]
	v_pk_mul_f32 v[10:11], v[84:85], v[10:11]
	v_mad_u32_u24 v80, v202, s77, v196
	v_ashrrev_i32_e32 v87, 31, v86
	v_readlane_b32 s36, v254, 54
	s_lshl_b32 s0, s16, 8
	v_readlane_b32 s3, v254, 33
	v_pk_mul_f32 v[12:13], v[160:161], v[12:13]
	v_pk_mul_f32 v[14:15], v[162:163], v[14:15]
	v_pk_mul_f32 v[164:165], v[152:153], v[164:165]
	v_pk_mul_f32 v[166:167], v[154:155], v[166:167]
	v_pk_mul_f32 v[168:169], v[156:157], v[168:169]
	v_pk_mul_f32 v[170:171], v[158:159], v[170:171]
	ds_write_b128 v80, v[8:11]
	ds_write_b128 v80, v[12:15] offset:64
	ds_write_b128 v80, v[164:167] offset:128
	ds_write_b128 v80, v[168:171] offset:192
	v_lshlrev_b64 v[8:9], 11, v[86:87]
	v_readlane_b32 s37, v254, 55
	s_or_b32 s60, s3, s0
	v_and_b32_e32 v10, 7, v194
	v_lshl_add_u64 v[8:9], v[8:9], 0, s[36:37]
	s_lshl_b64 s[36:37], s[60:61], 1
	v_lshlrev_b32_e32 v80, 4, v10
	s_add_u32 s36, s18, s36
	s_nop 1
	v_lshl_add_u64 v[8:9], v[8:9], 0, v[80:81]
	s_addc_u32 s37, s19, s37
	v_lshl_add_u64 v[8:9], s[36:37], 0, v[8:9]
	s_mov_b64 s[36:37], 0x590f200
	v_mul_lo_u32 v11, v86, s77
	v_lshlrev_b32_e32 v10, 5, v10
	v_lshl_add_u64 v[8:9], v[8:9], 0, s[36:37]
	v_add3_u32 v10, v11, v10, s50
	s_mov_b32 s0, 0
	s_mov_b64 s[36:37], 0x4000
	v_add_u32_e32 v11, s0, v10
	v_add_u32_e32 v12, 0x10000, v11
	v_add_u32_e32 v11, 0x10010, v11
	ds_read_b128 v[12:15], v12
	ds_read_b128 v[164:167], v11

.LBB0_790:
	s_or_b64 exec, exec, s[44:45]
	s_waitcnt lgkmcnt(0)
	ds_read_b128 v[8:11], v201 offset:256
	ds_read_b128 v[12:15], v201 offset:320
	ds_read_b128 v[164:167], v201 offset:384
	ds_read_b128 v[168:171], v201 offset:448
	s_lshl_b32 s0, s16, 8
	v_readlane_b32 s3, v254, 33
	s_waitcnt lgkmcnt(0)
	v_pk_mul_f32 v[10:11], v[84:85], v[10:11]
	v_pk_mul_f32 v[8:9], v[82:83], v[8:9]
	v_mad_u32_u24 v80, v202, s77, v196
	v_ashrrev_i32_e32 v87, 31, v86
	s_or_b32 s60, s3, s0
	v_pk_mul_f32 v[14:15], v[162:163], v[14:15]
	v_pk_mul_f32 v[12:13], v[160:161], v[12:13]
	v_pk_mul_f32 v[166:167], v[154:155], v[166:167]
	v_pk_mul_f32 v[164:165], v[152:153], v[164:165]
	v_pk_mul_f32 v[170:171], v[158:159], v[170:171]
	v_pk_mul_f32 v[168:169], v[156:157], v[168:169]
	ds_write_b128 v80, v[8:11]
	ds_write_b128 v80, v[12:15] offset:64
	ds_write_b128 v80, v[164:167] offset:128
	ds_write_b128 v80, v[168:171] offset:192
	v_lshlrev_b64 v[8:9], 9, v[86:87]
	v_and_b32_e32 v10, 7, v194
	s_lshl_b64 s[36:37], s[60:61], 1
	v_lshl_add_u64 v[8:9], v[8:9], 0, s[8:9]
	v_lshlrev_b32_e32 v80, 4, v10
	s_add_u32 s36, s18, s36
	v_lshl_add_u64 v[8:9], v[8:9], 0, v[80:81]
	s_addc_u32 s37, s19, s37
	s_nop 1
	v_lshl_add_u64 v[8:9], s[36:37], 0, v[8:9]
	s_mov_b64 s[36:37], 0x5203500
	v_lshl_add_u64 v[164:165], v[8:9], 0, s[36:37]
	v_mul_lo_u32 v8, v86, s77
	v_lshlrev_b32_e32 v9, 5, v10
	v_add3_u32 v80, v8, v9, s50
	s_mov_b32 s0, 0
	v_add_u32_e32 v8, s0, v80
	v_add_u32_e32 v9, 0x10000, v8
	v_add_u32_e32 v12, 0x10010, v8
	ds_read_b128 v[8:11], v9
	ds_read_b128 v[12:15], v12

.LBB0_820:
	v_mad_u32_u24 v80, v202, s77, v196
	ds_write_b128 v80, v[8:11]
	ds_write_b128 v80, v[164:167] offset:64
	ds_write_b128 v80, v[12:15] offset:128
	ds_write_b128 v80, v[168:171] offset:192
	v_mov_b64_e32 v[8:9], s[28:29]
	s_movk_i32 s0, 0x300
	v_mad_i64_i32 v[8:9], s[2:3], v86, s0, v[8:9]
	s_lshl_b32 s0, s16, 8
	v_readlane_b32 s2, v254, 33
	s_or_b32 s60, s2, s0
	v_and_b32_e32 v10, 7, v194
	s_lshl_b64 s[2:3], s[60:61], 1
	v_lshlrev_b32_e32 v80, 4, v10
	s_add_u32 s2, s18, s2
	v_lshl_add_u64 v[8:9], v[8:9], 0, v[80:81]
	s_addc_u32 s3, s19, s3
	s_nop 1
	v_lshl_add_u64 v[8:9], s[2:3], 0, v[8:9]
	s_mov_b64 s[2:3], 0x4805a00
	v_lshl_add_u64 v[164:165], v[8:9], 0, s[2:3]
	v_mul_lo_u32 v8, v86, s77
	v_lshlrev_b32_e32 v9, 5, v10
	v_add3_u32 v80, v8, v9, s50
	s_mov_b32 s0, 0
	s_mov_b32 s2, 0x3e38aa3b
	v_add_u32_e32 v8, s0, v80
	v_add_u32_e32 v9, 0x10000, v8
	v_add_u32_e32 v12, 0x10010, v8
	ds_read_b128 v[8:11], v9
	ds_read_b128 v[12:15], v12

.LBB0_823:
	s_andn2_b64 vcc, exec, s[44:45]
	s_cbranch_vccnz .LBB0_826
	s_lshl_b32 s0, s16, 8
	v_readlane_b32 s2, v254, 33
	v_mad_u32_u24 v8, v202, s77, v196
	v_ashrrev_i32_e32 v87, 31, v86
	s_or_b32 s60, s2, s0
	ds_write_b128 v8, v[82:85]
	ds_write_b128 v8, v[160:163] offset:64
	ds_write_b128 v8, v[152:155] offset:128
	ds_write_b128 v8, v[156:159] offset:192
	v_lshlrev_b64 v[8:9], 9, v[86:87]
	v_and_b32_e32 v10, 7, v194
	s_lshl_b64 s[2:3], s[60:61], 1
	v_lshl_add_u64 v[8:9], v[8:9], 0, s[8:9]
	v_lshlrev_b32_e32 v80, 4, v10
	s_add_u32 s2, s18, s2
	v_lshl_add_u64 v[8:9], v[8:9], 0, v[80:81]
	s_addc_u32 s3, s19, s3
	s_nop 1
	v_lshl_add_u64 v[8:9], s[2:3], 0, v[8:9]
	s_mov_b64 s[2:3], 0x4403c00
	v_lshl_add_u64 v[164:165], v[8:9], 0, s[2:3]
	v_mul_lo_u32 v8, v86, s77
	v_lshlrev_b32_e32 v9, 5, v10
	v_add3_u32 v80, v8, v9, s50
	s_mov_b32 s0, 0
	v_add_u32_e32 v8, s0, v80
	v_add_u32_e32 v9, 0x10000, v8
	v_add_u32_e32 v12, 0x10010, v8
	ds_read_b128 v[8:11], v9
	ds_read_b128 v[12:15], v12

.LBB0_831:
	s_lshl_b32 s0, s16, 8
	v_readlane_b32 s2, v254, 33
	v_mad_u32_u24 v80, v202, s77, v196
	v_ashrrev_i32_e32 v87, 31, v86
	s_or_b32 s60, s2, s0
	ds_write_b128 v80, v[8:11]
	ds_write_b128 v80, v[12:15] offset:64
	ds_write_b128 v80, v[164:167] offset:128
	ds_write_b128 v80, v[168:171] offset:192
	v_lshlrev_b64 v[8:9], 9, v[86:87]
	v_and_b32_e32 v10, 7, v194
	s_lshl_b64 s[2:3], s[60:61], 1
	v_lshl_add_u64 v[8:9], v[8:9], 0, s[8:9]
	v_lshlrev_b32_e32 v80, 4, v10
	s_add_u32 s2, s18, s2
	v_lshl_add_u64 v[8:9], v[8:9], 0, v[80:81]
	s_addc_u32 s3, s19, s3
	s_nop 1
	v_lshl_add_u64 v[8:9], s[2:3], 0, v[8:9]
	s_mov_b64 s[2:3], 0x4003e00
	v_lshl_add_u64 v[164:165], v[8:9], 0, s[2:3]
	v_mul_lo_u32 v8, v86, s77
	v_lshlrev_b32_e32 v9, 5, v10
	v_add3_u32 v80, v8, v9, s50
	s_mov_b32 s0, 0
	s_mov_b32 s2, 0x3e000000
	v_add_u32_e32 v8, s0, v80
	v_add_u32_e32 v9, 0x10000, v8
	v_add_u32_e32 v12, 0x10010, v8
	ds_read_b128 v[8:11], v9
	ds_read_b128 v[12:15], v12

.LBB0_837:
	s_lshl_b32 s0, s16, 8
	v_readlane_b32 s2, v254, 33
	s_or_b32 s2, s2, s0
	v_mad_u32_u24 v8, v202, s77, v196
	v_ashrrev_i32_e32 v87, 31, v86
	s_ashr_i32 s3, s2, 31
	ds_write_b128 v8, v[82:85]
	ds_write_b128 v8, v[160:163] offset:64
	ds_write_b128 v8, v[152:155] offset:128
	ds_write_b128 v8, v[156:159] offset:192
	v_lshlrev_b64 v[8:9], 9, v[86:87]
	v_and_b32_e32 v10, 7, v194
	s_lshl_b64 s[2:3], s[2:3], 1
	v_lshl_add_u64 v[8:9], v[8:9], 0, s[8:9]
	v_lshlrev_b32_e32 v80, 4, v10
	s_add_u32 s2, s18, s2
	s_nop 1
	v_lshl_add_u64 v[8:9], v[8:9], 0, v[80:81]
	s_addc_u32 s3, s19, s3
	v_lshl_add_u64 v[8:9], s[2:3], 0, v[8:9]
	s_mov_b64 s[2:3], 0x3c04000
	v_mul_lo_u32 v11, v86, s77
	v_lshlrev_b32_e32 v10, 5, v10
	v_lshl_add_u64 v[8:9], v[8:9], 0, s[2:3]
	v_add3_u32 v10, v11, v10, s50
	s_mov_b32 s0, 0
	v_add_u32_e32 v11, s0, v10
	v_add_u32_e32 v12, 0x10000, v11
	v_add_u32_e32 v11, 0x10010, v11
	ds_read_b128 v[12:15], v12
	ds_read_b128 v[82:85], v11

.LBB0_913:
	v_mov_b64_e32 v[14:15], v[6:7]
	s_andn2_b64 vcc, exec, s[44:45]
	v_mov_b64_e32 v[12:13], v[4:5]
	v_mov_b64_e32 v[10:11], v[2:3]
	v_mov_b64_e32 v[8:9], v[0:1]
	s_cbranch_vccnz .LBB0_922
	s_cmp_lg_u32 s58, 13
	s_mov_b64 s[44:45], -1
	s_cbranch_scc0 .LBB0_918
	v_mul_f32_e32 v80, 0xbfb8aa3b, v152
	v_exp_f32_e32 v80, v80
	v_mul_f32_e32 v87, 0xbfb8aa3b, v153
	v_exp_f32_e32 v87, v87
	v_mul_f32_e32 v165, 0xbfb8aa3b, v155
	v_add_f32_e32 v80, 1.0, v80
	v_rcp_f32_e32 v164, v80
	v_add_f32_e32 v80, 1.0, v87
	v_mul_f32_e32 v87, 0xbfb8aa3b, v154
	v_exp_f32_e32 v87, v87
	v_exp_f32_e32 v167, v165
	v_rcp_f32_e32 v165, v80
	v_mul_f32_e32 v8, 0xbfb8aa3b, v82
	v_add_f32_e32 v80, 1.0, v87
	v_mul_f32_e32 v87, 0xbfb8aa3b, v156
	v_rcp_f32_e32 v166, v80
	v_add_f32_e32 v80, 1.0, v167
	v_exp_f32_e32 v87, v87
	v_mul_f32_e32 v167, 0xbfb8aa3b, v157
	v_exp_f32_e32 v169, v167
	v_mul_f32_e32 v9, 0xbfb8aa3b, v83
	v_mul_f32_e32 v10, 0xbfb8aa3b, v84
	v_mul_f32_e32 v11, 0xbfb8aa3b, v85
	v_rcp_f32_e32 v167, v80
	v_add_f32_e32 v80, 1.0, v87
	v_mul_f32_e32 v87, 0xbfb8aa3b, v158
	v_exp_f32_e32 v8, v8
	v_exp_f32_e32 v9, v9
	v_exp_f32_e32 v10, v10
	v_exp_f32_e32 v11, v11
	v_mul_f32_e32 v12, 0xbfb8aa3b, v160
	v_mul_f32_e32 v13, 0xbfb8aa3b, v161
	v_mul_f32_e32 v14, 0xbfb8aa3b, v162
	v_mul_f32_e32 v15, 0xbfb8aa3b, v163
	v_rcp_f32_e32 v168, v80
	v_add_f32_e32 v80, 1.0, v169
	v_exp_f32_e32 v87, v87
	v_mul_f32_e32 v169, 0xbfb8aa3b, v159
	v_exp_f32_e32 v12, v12
	v_exp_f32_e32 v13, v13
	v_exp_f32_e32 v14, v14
	v_exp_f32_e32 v15, v15
	v_exp_f32_e32 v171, v169
	v_add_f32_e32 v8, 1.0, v8
	v_add_f32_e32 v9, 1.0, v9
	v_add_f32_e32 v10, 1.0, v10
	v_add_f32_e32 v11, 1.0, v11
	v_rcp_f32_e32 v169, v80
	v_add_f32_e32 v80, 1.0, v87
	v_rcp_f32_e32 v8, v8
	v_rcp_f32_e32 v9, v9
	v_rcp_f32_e32 v10, v10
	v_rcp_f32_e32 v11, v11
	v_add_f32_e32 v12, 1.0, v12
	v_add_f32_e32 v13, 1.0, v13
	v_add_f32_e32 v14, 1.0, v14
	v_add_f32_e32 v15, 1.0, v15
	v_rcp_f32_e32 v170, v80
	v_add_f32_e32 v80, 1.0, v171
	v_rcp_f32_e32 v12, v12
	v_rcp_f32_e32 v13, v13
	v_rcp_f32_e32 v14, v14
	v_rcp_f32_e32 v15, v15
	v_rcp_f32_e32 v171, v80
	v_pk_mul_f32 v[8:9], v[82:83], v[8:9]
	v_pk_mul_f32 v[10:11], v[84:85], v[10:11]
	v_mad_u32_u24 v80, v202, s77, v196
	v_ashrrev_i32_e32 v87, 31, v86
	v_readlane_b32 s36, v254, 54
	s_lshl_b32 s0, s16, 8
	v_readlane_b32 s3, v254, 33
	v_pk_mul_f32 v[12:13], v[160:161], v[12:13]
	v_pk_mul_f32 v[14:15], v[162:163], v[14:15]
	v_pk_mul_f32 v[164:165], v[152:153], v[164:165]
	v_pk_mul_f32 v[166:167], v[154:155], v[166:167]
	v_pk_mul_f32 v[168:169], v[156:157], v[168:169]
	v_pk_mul_f32 v[170:171], v[158:159], v[170:171]
	ds_write_b128 v80, v[8:11]
	ds_write_b128 v80, v[12:15] offset:64
	ds_write_b128 v80, v[164:167] offset:128
	ds_write_b128 v80, v[168:171] offset:192
	v_lshlrev_b64 v[8:9], 11, v[86:87]
	v_readlane_b32 s37, v254, 55
	s_or_b32 s60, s3, s0
	v_and_b32_e32 v10, 7, v194
	v_lshl_add_u64 v[8:9], v[8:9], 0, s[36:37]
	s_lshl_b64 s[36:37], s[60:61], 1
	v_lshlrev_b32_e32 v80, 4, v10
	s_add_u32 s36, s18, s36
	s_nop 1
	v_lshl_add_u64 v[8:9], v[8:9], 0, v[80:81]
	s_addc_u32 s37, s19, s37
	v_lshl_add_u64 v[8:9], s[36:37], 0, v[8:9]
	s_mov_b64 s[36:37], 0x591f200
	v_mul_lo_u32 v11, v86, s77
	v_lshlrev_b32_e32 v10, 5, v10
	v_lshl_add_u64 v[8:9], v[8:9], 0, s[36:37]
	v_add3_u32 v10, v11, v10, s50
	s_mov_b32 s0, 0
	s_mov_b64 s[36:37], 0x4000
	v_add_u32_e32 v11, s0, v10
	v_add_u32_e32 v12, 0x10000, v11
	v_add_u32_e32 v11, 0x10010, v11
	ds_read_b128 v[12:15], v12
	ds_read_b128 v[164:167], v11

.LBB0_926:
	s_or_b64 exec, exec, s[44:45]
	s_waitcnt lgkmcnt(0)
	ds_read_b128 v[8:11], v201 offset:256
	ds_read_b128 v[12:15], v201 offset:320
	ds_read_b128 v[164:167], v201 offset:384
	ds_read_b128 v[168:171], v201 offset:448
	s_lshl_b32 s0, s16, 8
	v_readlane_b32 s3, v254, 33
	s_waitcnt lgkmcnt(0)
	v_pk_mul_f32 v[10:11], v[84:85], v[10:11]
	v_pk_mul_f32 v[8:9], v[82:83], v[8:9]
	v_mad_u32_u24 v80, v202, s77, v196
	v_ashrrev_i32_e32 v87, 31, v86
	s_or_b32 s60, s3, s0
	v_pk_mul_f32 v[14:15], v[162:163], v[14:15]
	v_pk_mul_f32 v[12:13], v[160:161], v[12:13]
	v_pk_mul_f32 v[166:167], v[154:155], v[166:167]
	v_pk_mul_f32 v[164:165], v[152:153], v[164:165]
	v_pk_mul_f32 v[170:171], v[158:159], v[170:171]
	v_pk_mul_f32 v[168:169], v[156:157], v[168:169]
	ds_write_b128 v80, v[8:11]
	ds_write_b128 v80, v[12:15] offset:64
	ds_write_b128 v80, v[164:167] offset:128
	ds_write_b128 v80, v[168:171] offset:192
	v_lshlrev_b64 v[8:9], 9, v[86:87]
	v_and_b32_e32 v10, 7, v194
	s_lshl_b64 s[36:37], s[60:61], 1
	v_lshl_add_u64 v[8:9], v[8:9], 0, s[8:9]
	v_lshlrev_b32_e32 v80, 4, v10
	s_add_u32 s36, s18, s36
	v_lshl_add_u64 v[8:9], v[8:9], 0, v[80:81]
	s_addc_u32 s37, s19, s37
	s_nop 1
	v_lshl_add_u64 v[8:9], s[36:37], 0, v[8:9]
	s_mov_b64 s[36:37], 0x5207500
	v_lshl_add_u64 v[164:165], v[8:9], 0, s[36:37]
	v_mul_lo_u32 v8, v86, s77
	v_lshlrev_b32_e32 v9, 5, v10
	v_add3_u32 v80, v8, v9, s50
	s_mov_b32 s0, 0
	v_add_u32_e32 v8, s0, v80
	v_add_u32_e32 v9, 0x10000, v8
	v_add_u32_e32 v12, 0x10010, v8
	ds_read_b128 v[8:11], v9
	ds_read_b128 v[12:15], v12

.LBB0_956:
	v_mad_u32_u24 v80, v202, s77, v196
	ds_write_b128 v80, v[8:11]
	ds_write_b128 v80, v[164:167] offset:64
	ds_write_b128 v80, v[12:15] offset:128
	ds_write_b128 v80, v[168:171] offset:192
	v_mov_b64_e32 v[8:9], s[28:29]
	s_movk_i32 s0, 0x300
	v_mad_i64_i32 v[8:9], s[2:3], v86, s0, v[8:9]
	s_lshl_b32 s0, s16, 8
	v_readlane_b32 s2, v254, 33
	s_or_b32 s60, s2, s0
	v_and_b32_e32 v10, 7, v194
	s_lshl_b64 s[2:3], s[60:61], 1
	v_lshlrev_b32_e32 v80, 4, v10
	s_add_u32 s2, s18, s2
	v_lshl_add_u64 v[8:9], v[8:9], 0, v[80:81]
	s_addc_u32 s3, s19, s3
	s_nop 1
	v_lshl_add_u64 v[8:9], s[2:3], 0, v[8:9]
	s_mov_b64 s[2:3], 0x480ba00
	v_lshl_add_u64 v[164:165], v[8:9], 0, s[2:3]
	v_mul_lo_u32 v8, v86, s77
	v_lshlrev_b32_e32 v9, 5, v10
	v_add3_u32 v80, v8, v9, s50
	s_mov_b32 s0, 0
	s_mov_b32 s2, 0x3e38aa3b
	v_add_u32_e32 v8, s0, v80
	v_add_u32_e32 v9, 0x10000, v8
	v_add_u32_e32 v12, 0x10010, v8
	ds_read_b128 v[8:11], v9
	ds_read_b128 v[12:15], v12

.LBB0_959:
	s_andn2_b64 vcc, exec, s[44:45]
	s_cbranch_vccnz .LBB0_962
	s_lshl_b32 s0, s16, 8
	v_readlane_b32 s2, v254, 33
	v_mad_u32_u24 v8, v202, s77, v196
	v_ashrrev_i32_e32 v87, 31, v86
	s_or_b32 s60, s2, s0
	ds_write_b128 v8, v[82:85]
	ds_write_b128 v8, v[160:163] offset:64
	ds_write_b128 v8, v[152:155] offset:128
	ds_write_b128 v8, v[156:159] offset:192
	v_lshlrev_b64 v[8:9], 9, v[86:87]
	v_and_b32_e32 v10, 7, v194
	s_lshl_b64 s[2:3], s[60:61], 1
	v_lshl_add_u64 v[8:9], v[8:9], 0, s[8:9]
	v_lshlrev_b32_e32 v80, 4, v10
	s_add_u32 s2, s18, s2
	v_lshl_add_u64 v[8:9], v[8:9], 0, v[80:81]
	s_addc_u32 s3, s19, s3
	s_nop 1
	v_lshl_add_u64 v[8:9], s[2:3], 0, v[8:9]
	s_mov_b64 s[2:3], 0x4407c00
	v_lshl_add_u64 v[164:165], v[8:9], 0, s[2:3]
	v_mul_lo_u32 v8, v86, s77
	v_lshlrev_b32_e32 v9, 5, v10
	v_add3_u32 v80, v8, v9, s50
	s_mov_b32 s0, 0
	v_add_u32_e32 v8, s0, v80
	v_add_u32_e32 v9, 0x10000, v8
	v_add_u32_e32 v12, 0x10010, v8
	ds_read_b128 v[8:11], v9
	ds_read_b128 v[12:15], v12

.LBB0_967:
	s_lshl_b32 s0, s16, 8
	v_readlane_b32 s2, v254, 33
	v_mad_u32_u24 v80, v202, s77, v196
	v_ashrrev_i32_e32 v87, 31, v86
	s_or_b32 s60, s2, s0
	ds_write_b128 v80, v[8:11]
	ds_write_b128 v80, v[12:15] offset:64
	ds_write_b128 v80, v[164:167] offset:128
	ds_write_b128 v80, v[168:171] offset:192
	v_lshlrev_b64 v[8:9], 9, v[86:87]
	v_and_b32_e32 v10, 7, v194
	s_lshl_b64 s[2:3], s[60:61], 1
	v_lshl_add_u64 v[8:9], v[8:9], 0, s[8:9]
	v_lshlrev_b32_e32 v80, 4, v10
	s_add_u32 s2, s18, s2
	v_lshl_add_u64 v[8:9], v[8:9], 0, v[80:81]
	s_addc_u32 s3, s19, s3
	s_nop 1
	v_lshl_add_u64 v[8:9], s[2:3], 0, v[8:9]
	s_mov_b64 s[2:3], 0x4007e00
	v_lshl_add_u64 v[164:165], v[8:9], 0, s[2:3]
	v_mul_lo_u32 v8, v86, s77
	v_lshlrev_b32_e32 v9, 5, v10
	v_add3_u32 v80, v8, v9, s50
	s_mov_b32 s0, 0
	s_mov_b32 s2, 0x3e000000
	v_add_u32_e32 v8, s0, v80
	v_add_u32_e32 v9, 0x10000, v8
	v_add_u32_e32 v12, 0x10010, v8
	ds_read_b128 v[8:11], v9
	ds_read_b128 v[12:15], v12

.LBB0_973:
	s_lshl_b32 s0, s16, 8
	v_readlane_b32 s2, v254, 33
	s_or_b32 s2, s2, s0
	v_mad_u32_u24 v8, v202, s77, v196
	v_ashrrev_i32_e32 v87, 31, v86
	s_ashr_i32 s3, s2, 31
	ds_write_b128 v8, v[82:85]
	ds_write_b128 v8, v[160:163] offset:64
	ds_write_b128 v8, v[152:155] offset:128
	ds_write_b128 v8, v[156:159] offset:192
	v_lshlrev_b64 v[8:9], 9, v[86:87]
	v_and_b32_e32 v10, 7, v194
	s_lshl_b64 s[2:3], s[2:3], 1
	v_lshl_add_u64 v[8:9], v[8:9], 0, s[8:9]
	v_lshlrev_b32_e32 v80, 4, v10
	s_add_u32 s2, s18, s2
	s_nop 1
	v_lshl_add_u64 v[8:9], v[8:9], 0, v[80:81]
	s_addc_u32 s3, s19, s3
	v_lshl_add_u64 v[8:9], s[2:3], 0, v[8:9]
	s_mov_b64 s[2:3], 0x3c08000
	v_mul_lo_u32 v11, v86, s77
	v_lshlrev_b32_e32 v10, 5, v10
	v_lshl_add_u64 v[8:9], v[8:9], 0, s[2:3]
	v_add3_u32 v10, v11, v10, s50
	s_mov_b32 s0, 0
	v_add_u32_e32 v11, s0, v10
	v_add_u32_e32 v12, 0x10000, v11
	v_add_u32_e32 v11, 0x10010, v11
	ds_read_b128 v[12:15], v12
	ds_read_b128 v[82:85], v11

.LBB0_1049:
	v_mov_b64_e32 v[14:15], v[6:7]
	s_andn2_b64 vcc, exec, s[44:45]
	v_mov_b64_e32 v[12:13], v[4:5]
	v_mov_b64_e32 v[10:11], v[2:3]
	v_mov_b64_e32 v[8:9], v[0:1]
	s_cbranch_vccnz .LBB0_1058
	s_cmp_lg_u32 s58, 13
	s_mov_b64 s[44:45], -1
	s_cbranch_scc0 .LBB0_1054
	v_mul_f32_e32 v80, 0xbfb8aa3b, v152
	v_exp_f32_e32 v80, v80
	v_mul_f32_e32 v87, 0xbfb8aa3b, v153
	v_exp_f32_e32 v87, v87
	v_mul_f32_e32 v165, 0xbfb8aa3b, v155
	v_add_f32_e32 v80, 1.0, v80
	v_rcp_f32_e32 v164, v80
	v_add_f32_e32 v80, 1.0, v87
	v_mul_f32_e32 v87, 0xbfb8aa3b, v154
	v_exp_f32_e32 v87, v87
	v_exp_f32_e32 v167, v165
	v_rcp_f32_e32 v165, v80
	v_mul_f32_e32 v8, 0xbfb8aa3b, v82
	v_add_f32_e32 v80, 1.0, v87
	v_mul_f32_e32 v87, 0xbfb8aa3b, v156
	v_rcp_f32_e32 v166, v80
	v_add_f32_e32 v80, 1.0, v167
	v_exp_f32_e32 v87, v87
	v_mul_f32_e32 v167, 0xbfb8aa3b, v157
	v_exp_f32_e32 v169, v167
	v_mul_f32_e32 v9, 0xbfb8aa3b, v83
	v_mul_f32_e32 v10, 0xbfb8aa3b, v84
	v_mul_f32_e32 v11, 0xbfb8aa3b, v85
	v_rcp_f32_e32 v167, v80
	v_add_f32_e32 v80, 1.0, v87
	v_mul_f32_e32 v87, 0xbfb8aa3b, v158
	v_exp_f32_e32 v8, v8
	v_exp_f32_e32 v9, v9
	v_exp_f32_e32 v10, v10
	v_exp_f32_e32 v11, v11
	v_mul_f32_e32 v12, 0xbfb8aa3b, v160
	v_mul_f32_e32 v13, 0xbfb8aa3b, v161
	v_mul_f32_e32 v14, 0xbfb8aa3b, v162
	v_mul_f32_e32 v15, 0xbfb8aa3b, v163
	v_rcp_f32_e32 v168, v80
	v_add_f32_e32 v80, 1.0, v169
	v_exp_f32_e32 v87, v87
	v_mul_f32_e32 v169, 0xbfb8aa3b, v159
	v_exp_f32_e32 v12, v12
	v_exp_f32_e32 v13, v13
	v_exp_f32_e32 v14, v14
	v_exp_f32_e32 v15, v15
	v_exp_f32_e32 v171, v169
	v_add_f32_e32 v8, 1.0, v8
	v_add_f32_e32 v9, 1.0, v9
	v_add_f32_e32 v10, 1.0, v10
	v_add_f32_e32 v11, 1.0, v11
	v_rcp_f32_e32 v169, v80
	v_add_f32_e32 v80, 1.0, v87
	v_rcp_f32_e32 v8, v8
	v_rcp_f32_e32 v9, v9
	v_rcp_f32_e32 v10, v10
	v_rcp_f32_e32 v11, v11
	v_add_f32_e32 v12, 1.0, v12
	v_add_f32_e32 v13, 1.0, v13
	v_add_f32_e32 v14, 1.0, v14
	v_add_f32_e32 v15, 1.0, v15
	v_rcp_f32_e32 v170, v80
	v_add_f32_e32 v80, 1.0, v171
	v_rcp_f32_e32 v12, v12
	v_rcp_f32_e32 v13, v13
	v_rcp_f32_e32 v14, v14
	v_rcp_f32_e32 v15, v15
	v_rcp_f32_e32 v171, v80
	v_pk_mul_f32 v[8:9], v[82:83], v[8:9]
	v_pk_mul_f32 v[10:11], v[84:85], v[10:11]
	v_mad_u32_u24 v80, v202, s77, v196
	v_ashrrev_i32_e32 v87, 31, v86
	v_readlane_b32 s26, v254, 54
	s_lshl_b32 s0, s16, 8
	v_readlane_b32 s3, v254, 33
	v_pk_mul_f32 v[12:13], v[160:161], v[12:13]
	v_pk_mul_f32 v[14:15], v[162:163], v[14:15]
	v_pk_mul_f32 v[164:165], v[152:153], v[164:165]
	v_pk_mul_f32 v[166:167], v[154:155], v[166:167]
	v_pk_mul_f32 v[168:169], v[156:157], v[168:169]
	v_pk_mul_f32 v[170:171], v[158:159], v[170:171]
	ds_write_b128 v80, v[8:11]
	ds_write_b128 v80, v[12:15] offset:64
	ds_write_b128 v80, v[164:167] offset:128
	ds_write_b128 v80, v[168:171] offset:192
	v_lshlrev_b64 v[8:9], 11, v[86:87]
	v_readlane_b32 s27, v254, 55
	s_or_b32 s60, s3, s0
	v_and_b32_e32 v10, 7, v194
	v_lshl_add_u64 v[8:9], v[8:9], 0, s[26:27]
	s_lshl_b64 s[26:27], s[60:61], 1
	v_lshlrev_b32_e32 v80, 4, v10
	s_add_u32 s26, s18, s26
	s_nop 1
	v_lshl_add_u64 v[8:9], v[8:9], 0, v[80:81]
	s_addc_u32 s27, s19, s27
	v_lshl_add_u64 v[8:9], s[26:27], 0, v[8:9]
	s_mov_b64 s[26:27], 0x592f200
	v_mul_lo_u32 v11, v86, s77
	v_lshlrev_b32_e32 v10, 5, v10
	v_lshl_add_u64 v[8:9], v[8:9], 0, s[26:27]
	v_add3_u32 v10, v11, v10, s50
	s_mov_b32 s0, 0
	s_mov_b64 s[26:27], 0x4000
	v_add_u32_e32 v11, s0, v10
	v_add_u32_e32 v12, 0x10000, v11
	v_add_u32_e32 v11, 0x10010, v11
	ds_read_b128 v[12:15], v12
	ds_read_b128 v[164:167], v11
.LBB0_1052:
	s_addk_i32 s0, 0x880
	s_waitcnt lgkmcnt(0)
	v_cvt_pk_bf16_f32 v168, v12, v13
	v_cvt_pk_bf16_f32 v169, v14, v15
	v_cvt_pk_bf16_f32 v170, v164, v165
	v_cvt_pk_bf16_f32 v171, v166, v167
	s_min_u32 s101, s0, 0x1980
	v_add_u32_e32 v11, s101, v10
	v_add_u32_e32 v12, 0x10000, v11
	v_add_u32_e32 v11, 0x10010, v11
	ds_read_b128 v[12:15], v12
	ds_read_b128 v[164:167], v11
	s_cmpk_eq_i32 s0, 0x2200
	global_store_dwordx4 v[8:9], v[168:171], off sc1
	s_nop 1
	v_lshl_add_u64 v[8:9], v[8:9], 0, s[26:27]
	s_cbranch_scc0 .LBB0_1052
	s_waitcnt lgkmcnt(0)
	s_mov_b64 s[44:45], 0

.LBB0_1062:
	s_or_b64 exec, exec, s[44:45]
	s_waitcnt lgkmcnt(0)
	ds_read_b128 v[8:11], v201 offset:256
	ds_read_b128 v[12:15], v201 offset:320
	ds_read_b128 v[164:167], v201 offset:384
	ds_read_b128 v[168:171], v201 offset:448
	s_lshl_b32 s0, s16, 8
	v_readlane_b32 s3, v254, 33
	s_waitcnt lgkmcnt(0)
	v_pk_mul_f32 v[10:11], v[84:85], v[10:11]
	v_pk_mul_f32 v[8:9], v[82:83], v[8:9]
	v_mad_u32_u24 v80, v202, s77, v196
	v_ashrrev_i32_e32 v87, 31, v86
	s_or_b32 s60, s3, s0
	v_pk_mul_f32 v[14:15], v[162:163], v[14:15]
	v_pk_mul_f32 v[12:13], v[160:161], v[12:13]
	v_pk_mul_f32 v[166:167], v[154:155], v[166:167]
	v_pk_mul_f32 v[164:165], v[152:153], v[164:165]
	v_pk_mul_f32 v[170:171], v[158:159], v[170:171]
	v_pk_mul_f32 v[168:169], v[156:157], v[168:169]
	ds_write_b128 v80, v[8:11]
	ds_write_b128 v80, v[12:15] offset:64
	ds_write_b128 v80, v[164:167] offset:128
	ds_write_b128 v80, v[168:171] offset:192
	v_lshlrev_b64 v[8:9], 9, v[86:87]
	v_and_b32_e32 v10, 7, v194
	s_lshl_b64 s[26:27], s[60:61], 1
	v_lshl_add_u64 v[8:9], v[8:9], 0, s[8:9]
	v_lshlrev_b32_e32 v80, 4, v10
	s_add_u32 s26, s18, s26
	v_lshl_add_u64 v[8:9], v[8:9], 0, v[80:81]
	s_addc_u32 s27, s19, s27
	s_nop 1
	v_lshl_add_u64 v[8:9], s[26:27], 0, v[8:9]
	s_mov_b64 s[26:27], 0x520b500
	v_lshl_add_u64 v[164:165], v[8:9], 0, s[26:27]
	v_mul_lo_u32 v8, v86, s77
	v_lshlrev_b32_e32 v9, 5, v10
	v_add3_u32 v80, v8, v9, s50
	s_mov_b32 s0, 0
	v_add_u32_e32 v8, s0, v80
	v_add_u32_e32 v9, 0x10000, v8
	v_add_u32_e32 v12, 0x10010, v8
	ds_read_b128 v[8:11], v9
	ds_read_b128 v[12:15], v12

.LBB0_1092:
	v_mad_u32_u24 v80, v202, s77, v196
	ds_write_b128 v80, v[8:11]
	ds_write_b128 v80, v[164:167] offset:64
	ds_write_b128 v80, v[12:15] offset:128
	ds_write_b128 v80, v[168:171] offset:192
	v_mov_b64_e32 v[8:9], s[28:29]
	s_movk_i32 s0, 0x300
	v_mad_i64_i32 v[8:9], s[2:3], v86, s0, v[8:9]
	s_lshl_b32 s0, s16, 8
	v_readlane_b32 s2, v254, 33
	s_or_b32 s60, s2, s0
	v_and_b32_e32 v10, 7, v194
	s_lshl_b64 s[2:3], s[60:61], 1
	v_lshlrev_b32_e32 v80, 4, v10
	s_add_u32 s2, s18, s2
	v_lshl_add_u64 v[8:9], v[8:9], 0, v[80:81]
	s_addc_u32 s3, s19, s3
	s_nop 1
	v_lshl_add_u64 v[8:9], s[2:3], 0, v[8:9]
	s_mov_b64 s[2:3], 0x4811a00
	v_lshl_add_u64 v[164:165], v[8:9], 0, s[2:3]
	v_mul_lo_u32 v8, v86, s77
	v_lshlrev_b32_e32 v9, 5, v10
	v_add3_u32 v80, v8, v9, s50
	s_mov_b32 s0, 0
	s_mov_b32 s2, 0x3e38aa3b
	v_add_u32_e32 v8, s0, v80
	v_add_u32_e32 v9, 0x10000, v8
	v_add_u32_e32 v12, 0x10010, v8
	ds_read_b128 v[8:11], v9
	ds_read_b128 v[12:15], v12

.LBB0_1095:
	s_andn2_b64 vcc, exec, s[44:45]
	s_cbranch_vccnz .LBB0_1098
	s_lshl_b32 s0, s16, 8
	v_readlane_b32 s2, v254, 33
	v_mad_u32_u24 v8, v202, s77, v196
	v_ashrrev_i32_e32 v87, 31, v86
	s_or_b32 s60, s2, s0
	ds_write_b128 v8, v[82:85]
	ds_write_b128 v8, v[160:163] offset:64
	ds_write_b128 v8, v[152:155] offset:128
	ds_write_b128 v8, v[156:159] offset:192
	v_lshlrev_b64 v[8:9], 9, v[86:87]
	v_and_b32_e32 v10, 7, v194
	s_lshl_b64 s[2:3], s[60:61], 1
	v_lshl_add_u64 v[8:9], v[8:9], 0, s[8:9]
	v_lshlrev_b32_e32 v80, 4, v10
	s_add_u32 s2, s18, s2
	v_lshl_add_u64 v[8:9], v[8:9], 0, v[80:81]
	s_addc_u32 s3, s19, s3
	s_nop 1
	v_lshl_add_u64 v[8:9], s[2:3], 0, v[8:9]
	s_mov_b64 s[2:3], 0x440bc00
	v_lshl_add_u64 v[164:165], v[8:9], 0, s[2:3]
	v_mul_lo_u32 v8, v86, s77
	v_lshlrev_b32_e32 v9, 5, v10
	v_add3_u32 v80, v8, v9, s50
	s_mov_b32 s0, 0
	v_add_u32_e32 v8, s0, v80
	v_add_u32_e32 v9, 0x10000, v8
	v_add_u32_e32 v12, 0x10010, v8
	ds_read_b128 v[8:11], v9
	ds_read_b128 v[12:15], v12

.LBB0_1103:
	s_lshl_b32 s0, s16, 8
	v_readlane_b32 s2, v254, 33
	v_mad_u32_u24 v80, v202, s77, v196
	v_ashrrev_i32_e32 v87, 31, v86
	s_or_b32 s60, s2, s0
	ds_write_b128 v80, v[8:11]
	ds_write_b128 v80, v[12:15] offset:64
	ds_write_b128 v80, v[164:167] offset:128
	ds_write_b128 v80, v[168:171] offset:192
	v_lshlrev_b64 v[8:9], 9, v[86:87]
	v_and_b32_e32 v10, 7, v194
	s_lshl_b64 s[2:3], s[60:61], 1
	v_lshl_add_u64 v[8:9], v[8:9], 0, s[8:9]
	v_lshlrev_b32_e32 v80, 4, v10
	s_add_u32 s2, s18, s2
	v_lshl_add_u64 v[8:9], v[8:9], 0, v[80:81]
	s_addc_u32 s3, s19, s3
	s_nop 1
	v_lshl_add_u64 v[8:9], s[2:3], 0, v[8:9]
	s_mov_b64 s[2:3], 0x400be00
	v_lshl_add_u64 v[164:165], v[8:9], 0, s[2:3]
	v_mul_lo_u32 v8, v86, s77
	v_lshlrev_b32_e32 v9, 5, v10
	v_add3_u32 v80, v8, v9, s50
	s_mov_b32 s0, 0
	s_mov_b32 s2, 0x3e000000
	v_add_u32_e32 v8, s0, v80
	v_add_u32_e32 v9, 0x10000, v8
	v_add_u32_e32 v12, 0x10010, v8
	ds_read_b128 v[8:11], v9
	ds_read_b128 v[12:15], v12

.LBB0_1109:
	s_lshl_b32 s0, s16, 8
	v_readlane_b32 s2, v254, 33
	s_or_b32 s2, s2, s0
	v_mad_u32_u24 v8, v202, s77, v196
	v_ashrrev_i32_e32 v87, 31, v86
	s_ashr_i32 s3, s2, 31
	ds_write_b128 v8, v[82:85]
	ds_write_b128 v8, v[160:163] offset:64
	ds_write_b128 v8, v[152:155] offset:128
	ds_write_b128 v8, v[156:159] offset:192
	v_lshlrev_b64 v[8:9], 9, v[86:87]
	v_and_b32_e32 v10, 7, v194
	s_lshl_b64 s[2:3], s[2:3], 1
	v_lshl_add_u64 v[8:9], v[8:9], 0, s[8:9]
	v_lshlrev_b32_e32 v80, 4, v10
	s_add_u32 s2, s18, s2
	s_nop 1
	v_lshl_add_u64 v[8:9], v[8:9], 0, v[80:81]
	s_addc_u32 s3, s19, s3
	v_lshl_add_u64 v[8:9], s[2:3], 0, v[8:9]
	s_mov_b64 s[2:3], 0x3c0c000
	v_mul_lo_u32 v11, v86, s77
	v_lshlrev_b32_e32 v10, 5, v10
	v_lshl_add_u64 v[8:9], v[8:9], 0, s[2:3]
	v_add3_u32 v10, v11, v10, s50
	s_mov_b32 s0, 0
	v_add_u32_e32 v11, s0, v10
	v_add_u32_e32 v12, 0x10000, v11
	v_add_u32_e32 v11, 0x10010, v11
	ds_read_b128 v[12:15], v12
	ds_read_b128 v[82:85], v11

.LBB0_1393:
	s_lshl_b32 s0, s0, 8
	v_mov_b32_e32 v66, v188
	s_and_b32 s0, s0, 0x600
	s_lshl_b32 s40, s79, 8
	s_and_b32 s40, s40, 0x100
	v_and_b32_e32 v65, -16, v66
	v_and_b32_e32 v64, 15, v66
	v_add_u32_e32 v73, s78, v65
	s_add_i32 s0, s66, s0
	v_mul_u32_u24_e32 v75, 0x110, v64
	v_mad_u32_u24 v64, v64, s77, v73
	s_add_i32 s0, s0, s40
	s_lshl_b32 s41, s79, 4
	ds_write_b128 v64, v[56:59]
	ds_write_b128 v64, v[60:63] offset:64
	ds_write_b128 v64, v[48:51] offset:128
	ds_write_b128 v64, v[52:55] offset:192
	s_mul_hi_i32 s40, s0, 0x600
	s_mulk_i32 s0, 0x600
	s_and_b32 s41, s41, 0xffffff80
	v_ashrrev_i32_e32 v71, 3, v66
	s_nop 1
	ds_write_b128 v64, v[40:43] offset:4352
	ds_write_b128 v64, v[44:47] offset:4416
	ds_write_b128 v64, v[32:35] offset:4480
	ds_write_b128 v64, v[36:39] offset:4544
	v_mov_b32_e32 v64, s0
	v_mov_b32_e32 v65, s40
	s_movk_i32 s0, 0x600
	s_add_i32 s60, s41, 0xffffea00
	v_mad_i64_i32 v[64:65], s[40:41], v71, s0, v[64:65]
	v_and_b32_e32 v77, 7, v66
	s_nop 1
	v_lshl_or_b32 v64, v77, 4, v64
	v_lshl_add_u64 v[64:65], s[60:61], 1, v[64:65]
	v_mul_lo_u32 v71, v71, s77
	v_lshlrev_b32_e32 v77, 5, v77
	v_lshl_add_u64 v[66:67], s[10:11], 0, v[64:65]
	v_add3_u32 v71, v71, v77, s73
	s_mov_b32 s0, 0
	v_add_u32_e32 v77, s0, v71
	v_add_u32_e32 v80, 0x10000, v77
	v_add_u32_e32 v77, 0x10010, v77
	ds_read_b128 v[82:85], v80
	ds_read_b128 v[86:89], v77
.LBB0_1394:
	s_addk_i32 s0, 0x880
	s_waitcnt lgkmcnt(0)
	v_cvt_pk_bf16_f32 v36, v82, v83
	v_cvt_pk_bf16_f32 v37, v84, v85
	v_cvt_pk_bf16_f32 v38, v86, v87
	v_cvt_pk_bf16_f32 v39, v88, v89
	s_min_u32 s101, s0, 0x1980
	v_add_u32_e32 v77, s101, v71
	v_add_u32_e32 v80, 0x10000, v77
	v_add_u32_e32 v77, 0x10010, v77
	ds_read_b128 v[82:85], v80
	ds_read_b128 v[86:89], v77
	s_cmpk_lg_i32 s0, 0x2200
	global_store_dwordx4 v[66:67], v[36:39], off sc1
	s_nop 1
	v_lshl_add_u64 v[66:67], v[66:67], 0, s[20:21]
	s_cbranch_scc1 .LBB0_1394
	s_waitcnt lgkmcnt(0)
	v_add_u32_e32 v66, v73, v75
	ds_write_b128 v66, v[24:27]
	ds_write_b128 v66, v[28:31] offset:64
	ds_write_b128 v66, v[16:19] offset:128
	ds_write_b128 v66, v[20:23] offset:192
	s_nop 1
	ds_write_b128 v66, v[8:11] offset:4352
	ds_write_b128 v66, v[12:15] offset:4416
	ds_write_b128 v66, v[0:3] offset:4480
	ds_write_b128 v66, v[4:7] offset:4544
	s_nop 1
	v_lshl_add_u64 v[64:65], s[12:13], 0, v[64:65]
	s_mov_b32 s0, 0
	v_add_u32_e32 v66, s0, v71
	v_add_u32_e32 v67, 0x10000, v66
	v_add_u32_e32 v66, 0x10010, v66
	ds_read_b128 v[82:85], v67
	ds_read_b128 v[86:89], v66
.LBB0_1396:
	s_addk_i32 s0, 0x880
	s_waitcnt lgkmcnt(0)
	v_cvt_pk_bf16_f32 v4, v82, v83
	v_cvt_pk_bf16_f32 v5, v84, v85
	v_cvt_pk_bf16_f32 v6, v86, v87
	v_cvt_pk_bf16_f32 v7, v88, v89
	s_min_u32 s101, s0, 0x1980
	v_add_u32_e32 v66, s101, v71
	v_add_u32_e32 v67, 0x10000, v66
	v_add_u32_e32 v66, 0x10010, v66
	ds_read_b128 v[82:85], v67
	ds_read_b128 v[86:89], v66
	s_cmpk_lg_i32 s0, 0x2200
	global_store_dwordx4 v[64:65], v[4:7], off sc1
	s_nop 1
	v_lshl_add_u64 v[64:65], v[64:65], 0, s[20:21]
	s_cbranch_scc1 .LBB0_1396
	s_waitcnt lgkmcnt(0)
	s_mov_b64 s[40:41], 0
.LBB0_1398:
	s_and_b64 vcc, exec, s[40:41]
	s_cbranch_vccz .LBB0_1403
	v_mov_b32_e32 v66, v188
	s_nop 1
	s_lshl_b32 s0, s79, 3
	v_and_b32_e32 v65, -16, v66
	v_and_b32_e32 v64, 15, v66
	v_add_u32_e32 v73, s78, v65
	v_mul_u32_u24_e32 v75, 0x110, v64
	v_mad_u32_u24 v64, v64, s77, v73
	ds_write_b128 v64, v[56:59]
	ds_write_b128 v64, v[60:63] offset:64
	ds_write_b128 v64, v[48:51] offset:128
	ds_write_b128 v64, v[52:55] offset:192
	s_nop 1
	ds_write_b128 v64, v[40:43] offset:4352
	ds_write_b128 v64, v[44:47] offset:4416
	ds_write_b128 v64, v[32:35] offset:4480
	ds_write_b128 v64, v[36:39] offset:4544
	s_and_b32 s0, s0, 0xf00
	v_ashrrev_i32_e32 v71, 3, v66
	s_nop 1
	v_mov_b32_e32 v80, s0
	s_movk_i32 s0, 0x600
	v_mad_i64_i32 v[64:65], s[40:41], v71, s0, v[80:81]
	v_and_b32_e32 v77, 7, v66
	v_lshl_or_b32 v64, v77, 4, v64
	v_mul_lo_u32 v71, v71, s77
	v_lshlrev_b32_e32 v77, 5, v77
	v_lshl_add_u64 v[66:67], s[18:19], 0, v[64:65]
	v_add3_u32 v71, v71, v77, s73
	s_mov_b32 s0, 0
	v_add_u32_e32 v77, s0, v71
	v_add_u32_e32 v80, 0x10000, v77
	v_add_u32_e32 v77, 0x10010, v77
	ds_read_b128 v[82:85], v80
	ds_read_b128 v[86:89], v77
.LBB0_1400:
	s_addk_i32 s0, 0x880
	s_waitcnt lgkmcnt(0)
	v_cvt_pk_bf16_f32 v36, v82, v83
	v_cvt_pk_bf16_f32 v37, v84, v85
	v_cvt_pk_bf16_f32 v38, v86, v87
	v_cvt_pk_bf16_f32 v39, v88, v89
	s_min_u32 s101, s0, 0x1980
	v_add_u32_e32 v77, s101, v71
	v_add_u32_e32 v80, 0x10000, v77
	v_add_u32_e32 v77, 0x10010, v77
	ds_read_b128 v[82:85], v80
	ds_read_b128 v[86:89], v77
	s_cmpk_lg_i32 s0, 0x2200
	global_store_dwordx4 v[66:67], v[36:39], off sc1
	s_nop 1
	v_lshl_add_u64 v[66:67], v[66:67], 0, s[20:21]
	s_cbranch_scc1 .LBB0_1400
	s_waitcnt lgkmcnt(0)
	v_add_u32_e32 v66, v73, v75
	ds_write_b128 v66, v[24:27]
	ds_write_b128 v66, v[28:31] offset:64
	ds_write_b128 v66, v[16:19] offset:128
	ds_write_b128 v66, v[20:23] offset:192
	s_nop 1
	ds_write_b128 v66, v[8:11] offset:4352
	ds_write_b128 v66, v[12:15] offset:4416
	ds_write_b128 v66, v[0:3] offset:4480
	ds_write_b128 v66, v[4:7] offset:4544
	s_nop 1
	v_lshl_add_u64 v[64:65], s[26:27], 0, v[64:65]
	s_mov_b32 s0, 0
	v_add_u32_e32 v66, s0, v71
	v_add_u32_e32 v67, 0x10000, v66
	v_add_u32_e32 v66, 0x10010, v66
	ds_read_b128 v[82:85], v67
	ds_read_b128 v[86:89], v66
.LBB0_1402:
	s_addk_i32 s0, 0x880
	s_waitcnt lgkmcnt(0)
	v_cvt_pk_bf16_f32 v4, v82, v83
	v_cvt_pk_bf16_f32 v5, v84, v85
	v_cvt_pk_bf16_f32 v6, v86, v87
	v_cvt_pk_bf16_f32 v7, v88, v89
	s_min_u32 s101, s0, 0x1980
	v_add_u32_e32 v66, s101, v71
	v_add_u32_e32 v67, 0x10000, v66
	v_add_u32_e32 v66, 0x10010, v66
	ds_read_b128 v[82:85], v67
	ds_read_b128 v[86:89], v66
	s_cmpk_eq_i32 s0, 0x2200
	global_store_dwordx4 v[64:65], v[4:7], off sc1
	s_nop 1
	v_lshl_add_u64 v[64:65], v[64:65], 0, s[20:21]
	s_cbranch_scc0 .LBB0_1402
	s_waitcnt lgkmcnt(0)
